# static s_setprio 1 for waves 4-7 during attention items (strategy lever 4), reset at mix loop top
# baseline (speedup 1.0000x reference)
; __device__ __forceinline__ int ltid() { int t = __builtin_amdgcn_workitem_id_x(); asm volatile("" : "+v"(t)); return t; }
; __device__ void phase_mix(PP p, int l, unsigned char* smem, unsigned* counter, int first_item) {
;     ...
;   for (;;) {
;     __syncthreads();
;     if (ltid() == 0) *qslot = atomicAdd(counter, 1u);
;     __syncthreads();
;     const int it = (int)*qslot + first_item;
;     if (it >= nitems) break;
.LBB0_256:
	s_setprio 0
	v_mov_b32_e32 v0, v228
	s_barrier
	s_nop 0
	v_cmp_eq_u32_e32 vcc, 0, v0
	s_and_saveexec_b64 s[4:5], vcc
	s_cbranch_execz .LBB0_260
	s_mov_b64 s[8:9], exec
	v_mbcnt_lo_u32_b32 v0, s8, 0
	v_mbcnt_hi_u32_b32 v0, s9, v0
	v_cmp_eq_u32_e32 vcc, 0, v0
	s_and_saveexec_b64 s[6:7], vcc
	s_cbranch_execz .LBB0_259
	s_bcnt1_i32_b64 s3, s[8:9]
	v_mov_b32_e32 v1, s3
	global_atomic_add v1, v[180:181], v1, off sc0

; __device__ void phase_mix(PP p, int l, unsigned char* smem, unsigned* counter, int first_item) {
;     ...
;     } else if (it < 1408 || (it >= 1664 && it < 1680)) {
;       int b, h, row0, nk;
;       if (it < 1408) { const int i2 = it - 1280; const int qt = i2 & 7; h = (i2 >> 3) & 3; b = i2 >> 5; row0 = b * SEQ + qt * 256; nk = NKEY; }
;       else { const int i2 = it - 1664; h = i2 & 3; b = i2 >> 2; row0 = NLAT + b * CTXL; nk = CTXL; }
;       ab::attn_body<true>((const bf16_t*)(ws + WS_GQ) + (size_t)row0 * 512 + h * 128, 512, (const bf16_t*)(ws + WS_GK) + (size_t)(b * 2 + (h >> 1)) * NKEY * 128,
;                           (const bf16_t*)(ws + WS_GVT) + (size_t)(b * 2 + (h >> 1)) * NKEY * 128, (bf16_t*)(ws + WS_MIX) + (size_t)row0 * D + 512 + h * 128, D, nk, (char*)smem);
.LBB0_269:
	v_readfirstlane_b32 s98, v228
	s_nop 3
	s_lshr_b32 s98, s98, 6
	s_cmp_ge_u32 s98, 4
	s_cbranch_scc0 .Lprio_skip
	s_setprio 1
